# fox_attn epilogue: head-norm row sums via DPP instead of ds_bpermute pairs, plus o_norm gain vector loaded once (v104 + foxepi + foxgain)
# speedup vs baseline: 1.0068x; 1.0022x over previous
.LBB0_161:
	s_or_b64 exec, exec, s[20:21]
	ds_bpermute_b32 v0, v187, v202
	s_lshl_b64 s[2:3], s[34:35], 2
	s_add_u32 s2, s48, s2
	s_mulk_i32 s54, 0x1200
	s_addc_u32 s3, s49, s3
	s_waitcnt lgkmcnt(0)
	v_add_f32_e32 v0, v202, v0
	v_div_scale_f32 v2, s[6:7], v0, v0, 1.0
	v_rcp_f32_e32 v3, v2
	s_add_i32 s6, s54, 0
	s_barrier
	v_fma_f32 v4, -v2, v3, 1.0
	v_fmac_f32_e32 v3, v4, v3
	v_div_scale_f32 v4, vcc, 1.0, v0, 1.0
	v_mul_f32_e32 v5, v4, v3
	v_fma_f32 v6, -v2, v5, v4
	v_fmac_f32_e32 v5, v6, v3
	v_fma_f32 v2, -v2, v5, v4
	v_div_fmas_f32 v2, v2, v3, v5
	v_div_fixup_f32 v0, v2, v0, 1.0
	v_pk_mul_f32 v[2:3], v[34:35], v[0:1] op_sel_hi:[1,0]
	v_pk_mul_f32 v[4:5], v[18:19], v[0:1] op_sel_hi:[1,0]
	v_pk_mul_f32 v[6:7], v[36:37], v[0:1] op_sel_hi:[1,0]
	v_pk_mul_f32 v[8:9], v[20:21], v[0:1] op_sel_hi:[1,0]
	v_pk_mul_f32 v[10:11], v[38:39], v[0:1] op_sel_hi:[1,0]
	v_pk_mul_f32 v[12:13], v[22:23], v[0:1] op_sel_hi:[1,0]
	v_pk_mul_f32 v[14:15], v[40:41], v[0:1] op_sel_hi:[1,0]
	v_pk_mul_f32 v[16:17], v[24:25], v[0:1] op_sel_hi:[1,0]
	v_pk_mul_f32 v[18:19], v[42:43], v[0:1] op_sel_hi:[1,0]
	v_pk_mul_f32 v[20:21], v[26:27], v[0:1] op_sel_hi:[1,0]
	v_pk_mul_f32 v[22:23], v[44:45], v[0:1] op_sel_hi:[1,0]
	v_pk_mul_f32 v[24:25], v[28:29], v[0:1] op_sel_hi:[1,0]
	v_pk_mul_f32 v[26:27], v[46:47], v[0:1] op_sel_hi:[1,0]
	v_pk_mul_f32 v[28:29], v[30:31], v[0:1] op_sel_hi:[1,0]
	v_pk_mul_f32 v[30:31], v[48:49], v[0:1] op_sel_hi:[1,0]
	v_pk_mul_f32 v[32:33], v[32:33], v[0:1] op_sel_hi:[1,0]
	v_mul_u32_u24_e32 v0, 0x90, v188
	v_add3_u32 v0, s6, v0, v191
	v_cvt_pk_bf16_f32 v2, v2, v3
	v_cvt_pk_bf16_f32 v3, v6, v7
	v_cvt_pk_bf16_f32 v6, v10, v11
	v_cvt_pk_bf16_f32 v7, v14, v15
	v_add_u32_e32 v0, 0x8000, v0
	ds_write2_b64 v0, v[2:3], v[6:7] offset1:2
	v_cvt_pk_bf16_f32 v2, v18, v19
	v_cvt_pk_bf16_f32 v3, v22, v23
	v_cvt_pk_bf16_f32 v6, v26, v27
	v_cvt_pk_bf16_f32 v7, v30, v31
	ds_write2_b64 v0, v[2:3], v[6:7] offset0:4 offset1:6
	v_cvt_pk_bf16_f32 v2, v4, v5
	v_cvt_pk_bf16_f32 v3, v8, v9
	v_cvt_pk_bf16_f32 v4, v12, v13
	v_cvt_pk_bf16_f32 v5, v16, v17
	ds_write2_b64 v0, v[2:3], v[4:5] offset0:8 offset1:10
	v_cvt_pk_bf16_f32 v2, v20, v21
	v_cvt_pk_bf16_f32 v3, v24, v25
	v_cvt_pk_bf16_f32 v4, v28, v29
	v_cvt_pk_bf16_f32 v5, v32, v33
	ds_write2_b64 v0, v[2:3], v[4:5] offset0:12 offset1:14
	v_lshlrev_b32_e32 v0, 3, v185
	v_lshrrev_b32_e32 v15, 3, v185
	v_and_b32_e32 v2, 56, v0
	s_lshl_b32 s7, s57, 2
	v_lshlrev_b32_e32 v0, 1, v2
	s_add_u32 s20, s2, s7
	v_lshlrev_b32_e32 v22, 2, v2
	v_mul_u32_u24_e32 v2, 0x90, v15
	s_waitcnt lgkmcnt(0)
	s_addc_u32 s21, s3, 0
	v_add3_u32 v14, s6, v0, v2
	ds_read_b128 v[2:5], v14 offset:32768
	global_load_dwordx4 v[64:67], v22, s[20:21]
	global_load_dwordx4 v[68:71], v22, s[20:21] offset:16
	ds_read_b128 v[10:13], v14 offset:33920
	s_mov_b32 s2, 0x358637bd
	s_waitcnt lgkmcnt(0)
	v_lshlrev_b32_e32 v32, 16, v2
	v_and_b32_e32 v33, 0xffff0000, v2
	v_lshlrev_b32_e32 v44, 16, v10
	v_and_b32_e32 v45, 0xffff0000, v10
	v_lshlrev_b32_e32 v28, 16, v3
	v_and_b32_e32 v29, 0xffff0000, v3
	v_pk_mul_f32 v[2:3], v[32:33], v[32:33]
	v_lshlrev_b32_e32 v40, 16, v11
	v_and_b32_e32 v41, 0xffff0000, v11
	v_pk_mul_f32 v[10:11], v[44:45], v[44:45]
	v_pk_mul_f32 v[30:31], v[28:29], v[28:29]
	v_pk_mul_f32 v[42:43], v[40:41], v[40:41]
	v_mov_b32_e32 v46, v10
	v_mov_b32_e32 v47, v2
	v_mov_b32_e32 v2, v11
	v_lshlrev_b32_e32 v26, 16, v4
	v_and_b32_e32 v27, 0xffff0000, v4
	v_lshlrev_b32_e32 v38, 16, v12
	v_and_b32_e32 v39, 0xffff0000, v12
	v_pk_add_f32 v[2:3], v[46:47], v[2:3]
	v_mov_b32_e32 v10, v42
	v_mov_b32_e32 v11, v30
	v_lshlrev_b32_e32 v20, 16, v5
	v_and_b32_e32 v21, 0xffff0000, v5
	v_pk_mul_f32 v[4:5], v[26:27], v[26:27]
	v_lshlrev_b32_e32 v34, 16, v13
	v_and_b32_e32 v35, 0xffff0000, v13
	v_pk_mul_f32 v[12:13], v[38:39], v[38:39]
	v_pk_add_f32 v[2:3], v[10:11], v[2:3]
	v_mov_b32_e32 v30, v43
	v_pk_add_f32 v[2:3], v[30:31], v[2:3]
	v_mov_b32_e32 v10, v12
	v_mov_b32_e32 v11, v4
	v_pk_mul_f32 v[24:25], v[20:21], v[20:21]
	v_pk_mul_f32 v[36:37], v[34:35], v[34:35]
	v_pk_add_f32 v[2:3], v[10:11], v[2:3]
	v_mov_b32_e32 v4, v13
	v_pk_add_f32 v[2:3], v[4:5], v[2:3]
	v_mov_b32_e32 v4, v36
	v_mov_b32_e32 v5, v24
	v_pk_add_f32 v[2:3], v[4:5], v[2:3]
	v_mov_b32_e32 v24, v37
	v_pk_add_f32 v[2:3], v[24:25], v[2:3]
	v_mov_b64_e32 v[12:13], s[2:3]
	s_mov_b32 s2, 0x3c800000
	v_or_b32_e32 v10, s55, v15
	v_mov_b32_e32 v11, s56
	s_waitcnt lgkmcnt(0)
	s_nop 1
	v_add_f32_dpp v2, v2, v2 quad_perm:[1,0,3,2] row_mask:0xf bank_mask:0xf
	v_add_f32_dpp v3, v3, v3 quad_perm:[1,0,3,2] row_mask:0xf bank_mask:0xf
	v_lshlrev_b64 v[24:25], 11, v[10:11]
	s_waitcnt lgkmcnt(0)
	s_nop 1
	v_add_f32_dpp v2, v2, v2 quad_perm:[2,3,0,1] row_mask:0xf bank_mask:0xf
	v_add_f32_dpp v3, v3, v3 quad_perm:[2,3,0,1] row_mask:0xf bank_mask:0xf
	s_waitcnt lgkmcnt(0)
	s_nop 1
	v_add_f32_dpp v2, v2, v2 row_half_mirror row_mask:0xf bank_mask:0xf
	v_add_f32_dpp v3, v3, v3 row_half_mirror row_mask:0xf bank_mask:0xf
	s_nop 0
	v_pk_fma_f32 v[30:31], v[2:3], s[2:3], v[12:13] op_sel_hi:[1,0,0]
	s_nop 0
	v_mul_f32_e32 v2, 0x4b800000, v31
	v_cmp_gt_f32_e32 vcc, s96, v31
	v_mul_f32_e32 v15, 0x4b800000, v30
	s_nop 0
	v_cndmask_b32_e32 v2, v31, v2, vcc
	v_rsq_f32_e32 v4, v2
	v_lshl_add_u64 v[2:3], s[74:75], 0, v[24:25]
	v_lshl_add_u64 v[2:3], v[2:3], 0, s[80:81]
	v_lshl_add_u64 v[24:25], v[2:3], 0, v[0:1]
	v_mul_f32_e32 v2, 0x45800000, v4
	v_cndmask_b32_e32 v2, v4, v2, vcc
	v_pk_mul_f32 v[4:5], v[2:3], v[32:33] op_sel_hi:[0,1]
	s_waitcnt vmcnt(0)
	v_pk_mul_f32 v[4:5], v[64:65], v[4:5]
	v_pk_mul_f32 v[6:7], v[2:3], v[28:29] op_sel_hi:[0,1]
	v_pk_mul_f32 v[6:7], v[66:67], v[6:7]
	v_pk_mul_f32 v[8:9], v[2:3], v[26:27] op_sel_hi:[0,1]
	v_pk_mul_f32 v[2:3], v[2:3], v[20:21] op_sel_hi:[0,1]
	v_pk_mul_f32 v[8:9], v[68:69], v[8:9]
	v_pk_mul_f32 v[16:17], v[70:71], v[2:3]
	v_cvt_pk_bf16_f32 v2, v4, v5
	v_cvt_pk_bf16_f32 v3, v6, v7
	v_cvt_pk_bf16_f32 v4, v8, v9
	v_cvt_pk_bf16_f32 v5, v16, v17
	global_store_dwordx4 v[24:25], v[2:5], off offset:512
	s_nop 0
	v_cmp_gt_f32_e32 vcc, s96, v30
	v_mov_b32_e32 v17, s56
	v_or_b32_e32 v16, 8, v10
	v_cndmask_b32_e32 v15, v30, v15, vcc
	v_rsq_f32_e32 v15, v15
	v_lshlrev_b64 v[16:17], 11, v[16:17]
	v_lshl_add_u64 v[16:17], s[74:75], 0, v[16:17]
	v_lshl_add_u64 v[16:17], v[16:17], 0, s[80:81]
	v_mul_f32_e32 v23, 0x45800000, v15
	v_cndmask_b32_e32 v24, v15, v23, vcc
	v_pk_mul_f32 v[26:27], v[24:25], v[44:45] op_sel_hi:[0,1]
	v_pk_mul_f32 v[28:29], v[24:25], v[40:41] op_sel_hi:[0,1]
	v_pk_mul_f32 v[30:31], v[24:25], v[38:39] op_sel_hi:[0,1]
	v_pk_mul_f32 v[24:25], v[24:25], v[34:35] op_sel_hi:[0,1]
	v_lshl_add_u64 v[20:21], v[16:17], 0, v[0:1]
	ds_read_b128 v[16:19], v14 offset:35072
	s_waitcnt lgkmcnt(0)
	v_lshlrev_b32_e32 v34, 16, v16
	v_and_b32_e32 v35, 0xffff0000, v16
	v_lshlrev_b32_e32 v32, 16, v17
	v_and_b32_e32 v33, 0xffff0000, v17
	v_pk_mul_f32 v[38:39], v[34:35], v[34:35]
	v_pk_mul_f32 v[36:37], v[32:33], v[32:33]
	v_mov_b32_e32 v49, v38
	v_pk_mul_f32 v[2:3], v[64:65], v[26:27]
	v_pk_mul_f32 v[4:5], v[66:67], v[28:29]
	v_pk_mul_f32 v[6:7], v[68:69], v[30:31]
	v_pk_mul_f32 v[8:9], v[70:71], v[24:25]
	v_cvt_pk_bf16_f32 v2, v2, v3
	v_cvt_pk_bf16_f32 v3, v4, v5
	v_cvt_pk_bf16_f32 v4, v6, v7
	v_cvt_pk_bf16_f32 v5, v8, v9
	global_store_dwordx4 v[20:21], v[2:5], off offset:512
	s_nop 0
	ds_read_b128 v[24:27], v14 offset:36224
	v_lshlrev_b32_e32 v28, 16, v19
	v_and_b32_e32 v29, 0xffff0000, v19
	v_lshlrev_b32_e32 v30, 16, v18
	v_and_b32_e32 v31, 0xffff0000, v18
	s_waitcnt lgkmcnt(0)
	v_lshlrev_b32_e32 v20, 16, v24
	v_and_b32_e32 v21, 0xffff0000, v24
	v_lshlrev_b32_e32 v18, 16, v25
	v_and_b32_e32 v19, 0xffff0000, v25
	v_pk_mul_f32 v[46:47], v[20:21], v[20:21]
	v_pk_mul_f32 v[44:45], v[18:19], v[18:19]
	v_mov_b32_e32 v48, v46
	v_mov_b32_e32 v38, v47
	v_lshlrev_b32_e32 v16, 16, v26
	v_and_b32_e32 v17, 0xffff0000, v26
	v_mov_b32_e32 v46, v44
	v_mov_b32_e32 v47, v36
	v_pk_add_f32 v[38:39], v[48:49], v[38:39]
	v_lshlrev_b32_e32 v14, 16, v27
	v_and_b32_e32 v15, 0xffff0000, v27
	v_pk_mul_f32 v[26:27], v[30:31], v[30:31]
	v_pk_mul_f32 v[42:43], v[16:17], v[16:17]
	v_mov_b32_e32 v36, v45
	v_pk_add_f32 v[38:39], v[46:47], v[38:39]
	v_mov_b32_e32 v44, v42
	v_mov_b32_e32 v45, v26
	v_pk_add_f32 v[36:37], v[36:37], v[38:39]
	v_pk_mul_f32 v[24:25], v[28:29], v[28:29]
	v_pk_mul_f32 v[40:41], v[14:15], v[14:15]
	v_mov_b32_e32 v26, v43
	v_pk_add_f32 v[36:37], v[44:45], v[36:37]
	v_mov_b32_e32 v42, v40
	v_mov_b32_e32 v43, v24
	v_pk_add_f32 v[26:27], v[26:27], v[36:37]
	v_mov_b32_e32 v24, v41
	v_pk_add_f32 v[26:27], v[42:43], v[26:27]
	v_mov_b32_e32 v37, s56
	v_pk_add_f32 v[24:25], v[24:25], v[26:27]
	v_or_b32_e32 v36, 16, v10
	v_lshlrev_b64 v[36:37], 11, v[36:37]
	v_or_b32_e32 v10, 24, v10
	v_lshlrev_b64 v[10:11], 11, v[10:11]
	s_waitcnt lgkmcnt(0)
	s_nop 1
	v_add_f32_dpp v24, v24, v24 quad_perm:[1,0,3,2] row_mask:0xf bank_mask:0xf
	v_add_f32_dpp v25, v25, v25 quad_perm:[1,0,3,2] row_mask:0xf bank_mask:0xf
	v_lshl_add_u64 v[10:11], s[74:75], 0, v[10:11]
	v_lshl_add_u64 v[10:11], v[10:11], 0, s[80:81]
	s_waitcnt lgkmcnt(0)
	s_nop 1
	v_add_f32_dpp v24, v24, v24 quad_perm:[2,3,0,1] row_mask:0xf bank_mask:0xf
	v_add_f32_dpp v25, v25, v25 quad_perm:[2,3,0,1] row_mask:0xf bank_mask:0xf
	s_waitcnt lgkmcnt(0)
	s_nop 1
	v_add_f32_dpp v24, v24, v24 row_half_mirror row_mask:0xf bank_mask:0xf
	v_add_f32_dpp v25, v25, v25 row_half_mirror row_mask:0xf bank_mask:0xf
	s_nop 0
	v_pk_fma_f32 v[12:13], v[24:25], s[2:3], v[12:13] op_sel_hi:[1,0,0]
	v_lshl_add_u64 v[24:25], s[74:75], 0, v[36:37]
	v_mul_f32_e32 v23, 0x4b800000, v13
	v_cmp_gt_f32_e32 vcc, s96, v13
	v_lshl_add_u64 v[24:25], v[24:25], 0, s[80:81]
	v_lshl_add_u64 v[24:25], v[24:25], 0, v[0:1]
	v_cndmask_b32_e32 v13, v13, v23, vcc
	v_rsq_f32_e32 v13, v13
	s_nop 0
	v_mul_f32_e32 v23, 0x45800000, v13
	v_cndmask_b32_e32 v26, v13, v23, vcc
	v_pk_mul_f32 v[34:35], v[26:27], v[34:35] op_sel_hi:[0,1]
	v_pk_mul_f32 v[32:33], v[26:27], v[32:33] op_sel_hi:[0,1]
	v_pk_mul_f32 v[30:31], v[26:27], v[30:31] op_sel_hi:[0,1]
	v_pk_mul_f32 v[26:27], v[26:27], v[28:29] op_sel_hi:[0,1]
	v_mul_f32_e32 v13, 0x4b800000, v12
	v_cmp_gt_f32_e32 vcc, s96, v12
	v_pk_mul_f32 v[28:29], v[68:69], v[30:31]
	v_pk_mul_f32 v[6:7], v[64:65], v[34:35]
	v_pk_mul_f32 v[8:9], v[66:67], v[32:33]
	v_pk_mul_f32 v[26:27], v[70:71], v[26:27]
	v_cvt_pk_bf16_f32 v2, v6, v7
	v_cvt_pk_bf16_f32 v3, v8, v9
	v_cvt_pk_bf16_f32 v4, v28, v29
	v_cvt_pk_bf16_f32 v5, v26, v27
	global_store_dwordx4 v[24:25], v[2:5], off offset:512
	s_nop 0
	v_cndmask_b32_e32 v12, v12, v13, vcc
	v_rsq_f32_e32 v12, v12
	s_nop 0
	v_mul_f32_e32 v13, 0x45800000, v12
	v_cndmask_b32_e32 v12, v12, v13, vcc
	v_pk_mul_f32 v[20:21], v[12:13], v[20:21] op_sel_hi:[0,1]
	v_pk_mul_f32 v[18:19], v[12:13], v[18:19] op_sel_hi:[0,1]
	v_pk_mul_f32 v[16:17], v[12:13], v[16:17] op_sel_hi:[0,1]
	v_pk_mul_f32 v[12:13], v[12:13], v[14:15] op_sel_hi:[0,1]
	v_pk_mul_f32 v[2:3], v[64:65], v[20:21]
	v_pk_mul_f32 v[4:5], v[66:67], v[18:19]
	v_pk_mul_f32 v[6:7], v[68:69], v[16:17]
	v_pk_mul_f32 v[8:9], v[70:71], v[12:13]
	v_cvt_pk_bf16_f32 v2, v2, v3
	v_cvt_pk_bf16_f32 v3, v4, v5
	v_cvt_pk_bf16_f32 v4, v6, v7
	v_cvt_pk_bf16_f32 v5, v8, v9
	v_lshl_add_u64 v[6:7], v[10:11], 0, v[0:1]
	global_store_dwordx4 v[6:7], v[2:5], off offset:512
